# pool_conv: the 16 conditional look-back loads per batch kept in flight together (one wait per batch)
# speedup vs baseline: 1.0259x; 1.0116x over previous
.LBB0_772:
	s_or_b64 exec, exec, s[4:5]
	s_waitcnt vmcnt(0)
	v_cvt_f32_f16_e32 v77, v140
	v_cvt_f32_f16_e32 v52, v141
	v_cvt_f32_f16_e32 v72, v142
	v_cvt_f32_f16_e32 v44, v143
	v_cvt_f32_f16_e32 v63, v144
	v_cvt_f32_f16_e32 v37, v145
	v_cvt_f32_f16_e32 v59, v146
	v_cvt_f32_f16_e32 v34, v147
	v_cvt_f32_f16_e32 v54, v148
	v_cvt_f32_f16_e32 v27, v149
	v_cvt_f32_f16_e32 v49, v150
	v_cvt_f32_f16_e32 v26, v151
	v_cvt_f32_f16_e32 v46, v152
	v_cvt_f32_f16_e32 v25, v153
	v_cvt_f32_f16_e32 v42, v154
	v_cvt_f32_f16_e32 v24, v155
	s_waitcnt vmcnt(15)
	v_cvt_f32_f16_e32 v20, v73
	v_min_u32_e32 v21, v81, v28
	v_cvt_f32_ubyte0_e32 v21, v21
	s_waitcnt vmcnt(14)
	v_cvt_f32_f16_e32 v69, v69
	v_add_f32_e32 v23, v23, v20
	v_sub_f32_e32 v23, v23, v77
	v_div_scale_f32 v73, s[4:5], v21, v21, v23
	v_rcp_f32_e32 v77, v73
	s_xor_b64 s[4:5], s[16:17], -1
	v_or_b32_e32 v81, s20, v17
	s_waitcnt vmcnt(13)
	v_cvt_f32_f16_e32 v65, v65
	v_fma_f32 v82, -v73, v77, 1.0
	v_fmac_f32_e32 v77, v82, v77
	v_div_scale_f32 v82, vcc, v23, v21, v23
	v_mul_f32_e32 v83, v82, v77
	v_fma_f32 v84, -v73, v83, v82
	v_fmac_f32_e32 v83, v84, v77
	v_fma_f32 v73, -v73, v83, v82
	v_div_fmas_f32 v73, v73, v77, v83
	v_div_fixup_f32 v21, v73, v21, v23
	v_sub_f32_e32 v20, v21, v20
	v_bfe_u32 v21, v20, 16, 1
	v_add3_u32 v73, v20, v21, s18
	v_add_f32_e32 v20, v23, v69
	v_sub_f32_e32 v23, v20, v52
	v_min_u32_e32 v20, v80, v28
	v_cvt_f32_ubyte0_e32 v52, v20
	v_div_scale_f32 v77, s[16:17], v52, v52, v23
	v_rcp_f32_e32 v80, v77
	v_mad_u64_u32 v[20:21], s[16:17], v81, s0, v[0:1]
	ds_write_b16_d16_hi v20, v73
	v_fma_f32 v21, -v77, v80, 1.0
	v_fmac_f32_e32 v80, v21, v80
	v_div_scale_f32 v21, vcc, v23, v52, v23
	v_mul_f32_e32 v73, v21, v80
	v_fma_f32 v81, -v77, v73, v21
	v_fmac_f32_e32 v73, v81, v80
	v_fma_f32 v21, -v77, v73, v21
	v_div_fmas_f32 v21, v21, v80, v73
	v_div_fixup_f32 v21, v21, v52, v23
	v_add_f32_e32 v23, v23, v65
	v_min_u32_e32 v52, v79, v28
	v_sub_f32_e32 v23, v23, v72
	v_cvt_f32_ubyte0_e32 v52, v52
	v_sub_f32_e32 v21, v21, v69
	v_div_scale_f32 v69, s[16:17], v52, v52, v23
	v_rcp_f32_e32 v72, v69
	v_bfe_u32 v73, v21, 16, 1
	v_add3_u32 v21, v21, v73, s18
	ds_write_b16_d16_hi v20, v21 offset:528
	v_fma_f32 v21, -v69, v72, 1.0
	v_fmac_f32_e32 v72, v21, v72
	v_div_scale_f32 v21, vcc, v23, v52, v23
	v_mul_f32_e32 v73, v21, v72
	v_fma_f32 v77, -v69, v73, v21
	s_waitcnt vmcnt(12)
	v_cvt_f32_f16_e32 v60, v60
	v_fmac_f32_e32 v73, v77, v72
	v_fma_f32 v21, -v69, v73, v21
	v_div_fmas_f32 v21, v21, v72, v73
	v_div_fixup_f32 v21, v21, v52, v23
	v_add_f32_e32 v23, v23, v60
	v_sub_f32_e32 v23, v23, v44
	v_min_u32_e32 v44, v78, v28
	v_cvt_f32_ubyte0_e32 v44, v44
	v_div_scale_f32 v52, s[16:17], v44, v44, v23
	v_sub_f32_e32 v21, v21, v65
	v_rcp_f32_e32 v65, v52
	v_bfe_u32 v69, v21, 16, 1
	v_add3_u32 v21, v21, v69, s18
	ds_write_b16_d16_hi v20, v21 offset:1056
	v_fma_f32 v21, -v52, v65, 1.0
	v_fmac_f32_e32 v65, v21, v65
	v_div_scale_f32 v21, vcc, v23, v44, v23
	v_mul_f32_e32 v69, v21, v65
	v_fma_f32 v72, -v52, v69, v21
	v_fmac_f32_e32 v69, v72, v65
	v_fma_f32 v21, -v52, v69, v21
	s_waitcnt vmcnt(11)
	v_cvt_f32_f16_e32 v52, v57
	v_div_fmas_f32 v21, v21, v65, v69
	v_div_fixup_f32 v21, v21, v44, v23
	v_min_u32_e32 v44, v76, v28
	v_add_f32_e32 v23, v23, v52
	v_sub_f32_e32 v23, v23, v63
	v_cvt_f32_ubyte0_e32 v44, v44
	v_div_scale_f32 v57, s[16:17], v44, v44, v23
	v_sub_f32_e32 v21, v21, v60
	v_rcp_f32_e32 v60, v57
	v_bfe_u32 v63, v21, 16, 1
	v_add3_u32 v21, v21, v63, s18
	ds_write_b16_d16_hi v20, v21 offset:1584
	v_fma_f32 v21, -v57, v60, 1.0
	v_fmac_f32_e32 v60, v21, v60
	v_div_scale_f32 v21, vcc, v23, v44, v23
	v_mul_f32_e32 v63, v21, v60
	v_fma_f32 v65, -v57, v63, v21
	s_waitcnt vmcnt(10)
	v_cvt_f32_f16_e32 v55, v55
	v_fmac_f32_e32 v63, v65, v60
	v_fma_f32 v21, -v57, v63, v21
	v_div_fmas_f32 v21, v21, v60, v63
	v_div_fixup_f32 v21, v21, v44, v23
	v_add_f32_e32 v23, v23, v55
	v_sub_f32_e32 v23, v23, v37
	v_min_u32_e32 v37, v75, v28
	v_cvt_f32_ubyte0_e32 v37, v37
	v_div_scale_f32 v44, s[16:17], v37, v37, v23
	v_sub_f32_e32 v21, v21, v52
	v_rcp_f32_e32 v52, v44
	v_bfe_u32 v57, v21, 16, 1
	v_add3_u32 v21, v21, v57, s18
	ds_write_b16_d16_hi v20, v21 offset:2112
	v_fma_f32 v21, -v44, v52, 1.0
	v_fmac_f32_e32 v52, v21, v52
	v_div_scale_f32 v21, vcc, v23, v37, v23
	v_mul_f32_e32 v57, v21, v52
	v_fma_f32 v60, -v44, v57, v21
	v_fmac_f32_e32 v57, v60, v52
	v_fma_f32 v21, -v44, v57, v21
	s_waitcnt vmcnt(9)
	v_cvt_f32_f16_e32 v44, v51
	v_div_fmas_f32 v21, v21, v52, v57
	v_div_fixup_f32 v21, v21, v37, v23
	v_min_u32_e32 v37, v74, v28
	v_add_f32_e32 v23, v23, v44
	v_sub_f32_e32 v23, v23, v59
	v_cvt_f32_ubyte0_e32 v37, v37
	v_div_scale_f32 v51, s[16:17], v37, v37, v23
	v_rcp_f32_e32 v52, v51
	v_sub_f32_e32 v21, v21, v55
	v_bfe_u32 v55, v21, 16, 1
	v_add3_u32 v21, v21, v55, s18
	ds_write_b16_d16_hi v20, v21 offset:2640
	v_fma_f32 v21, -v51, v52, 1.0
	v_fmac_f32_e32 v52, v21, v52
	v_div_scale_f32 v21, vcc, v23, v37, v23
	v_mul_f32_e32 v55, v21, v52
	v_fma_f32 v57, -v51, v55, v21
	s_waitcnt vmcnt(8)
	v_cvt_f32_f16_e32 v50, v50
	v_fmac_f32_e32 v55, v57, v52
	v_fma_f32 v21, -v51, v55, v21
	v_div_fmas_f32 v21, v21, v52, v55
	v_div_fixup_f32 v21, v21, v37, v23
	v_add_f32_e32 v23, v23, v50
	v_sub_f32_e32 v23, v23, v34
	v_min_u32_e32 v34, v71, v28
	v_cvt_f32_ubyte0_e32 v34, v34
	v_div_scale_f32 v37, s[16:17], v34, v34, v23
	v_sub_f32_e32 v21, v21, v44
	v_rcp_f32_e32 v44, v37
	v_bfe_u32 v51, v21, 16, 1
	v_add3_u32 v21, v21, v51, s18
	ds_write_b16_d16_hi v20, v21 offset:3168
	v_fma_f32 v21, -v37, v44, 1.0
	v_fmac_f32_e32 v44, v21, v44
	v_div_scale_f32 v21, vcc, v23, v34, v23
	v_mul_f32_e32 v51, v21, v44
	v_fma_f32 v52, -v37, v51, v21
	v_fmac_f32_e32 v51, v52, v44
	v_fma_f32 v21, -v37, v51, v21
	s_waitcnt vmcnt(7)
	v_cvt_f32_f16_e32 v37, v48
	v_div_fmas_f32 v21, v21, v44, v51
	v_div_fixup_f32 v21, v21, v34, v23
	v_min_u32_e32 v34, v70, v28
	v_add_f32_e32 v23, v23, v37
	v_sub_f32_e32 v23, v23, v54
	v_cvt_f32_ubyte0_e32 v34, v34
	v_div_scale_f32 v44, s[16:17], v34, v34, v23
	v_rcp_f32_e32 v48, v44
	v_sub_f32_e32 v21, v21, v50
	v_bfe_u32 v50, v21, 16, 1
	v_add3_u32 v21, v21, v50, s18
	ds_write_b16_d16_hi v20, v21 offset:3696
	v_fma_f32 v21, -v44, v48, 1.0
	v_fmac_f32_e32 v48, v21, v48
	v_div_scale_f32 v21, vcc, v23, v34, v23
	v_mul_f32_e32 v50, v21, v48
	v_fma_f32 v51, -v44, v50, v21
	v_fmac_f32_e32 v50, v51, v48
	v_fma_f32 v21, -v44, v50, v21
	s_waitcnt vmcnt(6)
	v_cvt_f32_f16_e32 v44, v47
	v_div_fmas_f32 v21, v21, v48, v50
	v_div_fixup_f32 v21, v21, v34, v23
	v_sub_f32_e32 v21, v21, v37
	v_add_f32_e32 v23, v23, v44
	v_sub_f32_e32 v23, v23, v27
	v_min_u32_e32 v27, v68, v28
	v_cvt_f32_ubyte0_e32 v27, v27
	v_div_scale_f32 v34, s[16:17], v27, v27, v23
	v_rcp_f32_e32 v37, v34
	v_bfe_u32 v47, v21, 16, 1
	v_add3_u32 v21, v21, v47, s18
	ds_write_b16_d16_hi v20, v21 offset:4224
	v_fma_f32 v21, -v34, v37, 1.0
	v_fmac_f32_e32 v37, v21, v37
	v_div_scale_f32 v21, vcc, v23, v27, v23
	v_mul_f32_e32 v47, v21, v37
	v_fma_f32 v48, -v34, v47, v21
	v_fmac_f32_e32 v47, v48, v37
	v_fma_f32 v21, -v34, v47, v21
	s_waitcnt vmcnt(5)
	v_cvt_f32_f16_e32 v34, v45
	v_div_fmas_f32 v21, v21, v37, v47
	v_div_fixup_f32 v21, v21, v27, v23
	v_min_u32_e32 v27, v62, v28
	v_add_f32_e32 v23, v23, v34
	v_sub_f32_e32 v23, v23, v49
	v_cvt_f32_ubyte0_e32 v27, v27
	v_div_scale_f32 v37, s[16:17], v27, v27, v23
	v_sub_f32_e32 v21, v21, v44
	v_rcp_f32_e32 v44, v37
	v_bfe_u32 v45, v21, 16, 1
	v_add3_u32 v21, v21, v45, s18
	ds_write_b16_d16_hi v20, v21 offset:4752
	v_fma_f32 v21, -v37, v44, 1.0
	v_fmac_f32_e32 v44, v21, v44
	v_div_scale_f32 v21, vcc, v23, v27, v23
	v_mul_f32_e32 v45, v21, v44
	v_fma_f32 v47, -v37, v45, v21
	v_fmac_f32_e32 v45, v47, v44
	v_fma_f32 v21, -v37, v45, v21
	s_waitcnt vmcnt(4)
	v_cvt_f32_f16_e32 v37, v43
	v_div_fmas_f32 v21, v21, v44, v45
	v_div_fixup_f32 v21, v21, v27, v23
	v_sub_f32_e32 v21, v21, v34
	v_add_f32_e32 v23, v23, v37
	v_sub_f32_e32 v23, v23, v26
	v_min_u32_e32 v26, v61, v28
	v_cvt_f32_ubyte0_e32 v26, v26
	v_div_scale_f32 v27, s[16:17], v26, v26, v23
	v_rcp_f32_e32 v34, v27
	v_bfe_u32 v43, v21, 16, 1
	v_add3_u32 v21, v21, v43, s18
	ds_write_b16_d16_hi v20, v21 offset:5280
	v_fma_f32 v21, -v27, v34, 1.0
	v_fmac_f32_e32 v34, v21, v34
	v_div_scale_f32 v21, vcc, v23, v26, v23
	v_mul_f32_e32 v43, v21, v34
	v_fma_f32 v44, -v27, v43, v21
	v_fmac_f32_e32 v43, v44, v34
	v_fma_f32 v21, -v27, v43, v21
	s_waitcnt vmcnt(3)
	v_cvt_f32_f16_e32 v27, v41
	v_div_fmas_f32 v21, v21, v34, v43
	v_div_fixup_f32 v21, v21, v26, v23
	v_min_u32_e32 v26, v58, v28
	v_add_f32_e32 v23, v23, v27
	v_sub_f32_e32 v23, v23, v46
	v_cvt_f32_ubyte0_e32 v26, v26
	v_div_scale_f32 v34, s[16:17], v26, v26, v23
	v_sub_f32_e32 v21, v21, v37
	v_rcp_f32_e32 v37, v34
	v_bfe_u32 v41, v21, 16, 1
	v_add3_u32 v21, v21, v41, s18
	ds_write_b16_d16_hi v20, v21 offset:5808
	v_fma_f32 v21, -v34, v37, 1.0
	v_fmac_f32_e32 v37, v21, v37
	v_div_scale_f32 v21, vcc, v23, v26, v23
	v_mul_f32_e32 v41, v21, v37
	v_fma_f32 v43, -v34, v41, v21
	v_fmac_f32_e32 v41, v43, v37
	v_fma_f32 v21, -v34, v41, v21
	s_waitcnt vmcnt(2)
	v_cvt_f32_f16_e32 v34, v40
	v_div_fmas_f32 v21, v21, v37, v41
	v_div_fixup_f32 v21, v21, v26, v23
	v_sub_f32_e32 v21, v21, v27
	v_add_f32_e32 v23, v23, v34
	v_sub_f32_e32 v23, v23, v25
	v_min_u32_e32 v25, v56, v28
	v_cvt_f32_ubyte0_e32 v25, v25
	v_div_scale_f32 v26, s[16:17], v25, v25, v23
	v_rcp_f32_e32 v27, v26
	v_bfe_u32 v37, v21, 16, 1
	v_add3_u32 v21, v21, v37, s18
	ds_write_b16_d16_hi v20, v21 offset:6336
	v_fma_f32 v21, -v26, v27, 1.0
	v_fmac_f32_e32 v27, v21, v27
	v_div_scale_f32 v21, vcc, v23, v25, v23
	v_mul_f32_e32 v37, v21, v27
	v_fma_f32 v40, -v26, v37, v21
	v_fmac_f32_e32 v37, v40, v27
	v_fma_f32 v21, -v26, v37, v21
	s_waitcnt vmcnt(1)
	v_cvt_f32_f16_e32 v26, v36
	v_div_fmas_f32 v21, v21, v27, v37
	v_div_fixup_f32 v21, v21, v25, v23
	v_min_u32_e32 v25, v53, v28
	v_add_f32_e32 v23, v23, v26
	v_sub_f32_e32 v23, v23, v42
	v_cvt_f32_ubyte0_e32 v25, v25
	v_div_scale_f32 v27, s[16:17], v25, v25, v23
	v_sub_f32_e32 v21, v21, v34
	v_rcp_f32_e32 v34, v27
	v_bfe_u32 v36, v21, 16, 1
	v_add3_u32 v21, v21, v36, s18
	ds_write_b16_d16_hi v20, v21 offset:6864
	v_fma_f32 v21, -v27, v34, 1.0
	v_fmac_f32_e32 v34, v21, v34
	v_div_scale_f32 v21, vcc, v23, v25, v23
	v_mul_f32_e32 v36, v21, v34
	v_fma_f32 v37, -v27, v36, v21
	v_fmac_f32_e32 v36, v37, v34
	v_fma_f32 v21, -v27, v36, v21
	s_waitcnt vmcnt(0)
	v_cvt_f32_f16_e32 v27, v35
	v_div_fmas_f32 v21, v21, v34, v36
	v_add_u32_e32 v22, 16, v22
	v_div_fixup_f32 v21, v21, v25, v23
	v_add_f32_e32 v23, v23, v27
	v_min_u32_e32 v22, v22, v28
	v_sub_f32_e32 v23, v23, v24
	v_cvt_f32_ubyte0_e32 v22, v22
	v_div_scale_f32 v24, s[16:17], v22, v22, v23
	v_sub_f32_e32 v21, v21, v26
	v_rcp_f32_e32 v26, v24
	v_bfe_u32 v25, v21, 16, 1
	v_add3_u32 v21, v21, v25, s18
	ds_write_b16_d16_hi v20, v21 offset:7392
	v_fma_f32 v21, -v24, v26, 1.0
	v_fmac_f32_e32 v26, v21, v26
	v_div_scale_f32 v21, vcc, v23, v22, v23
	v_mul_f32_e32 v25, v21, v26
	v_fma_f32 v34, -v24, v25, v21
	v_fmac_f32_e32 v25, v34, v26
	v_fma_f32 v21, -v24, v25, v21
	v_div_fmas_f32 v21, v21, v26, v25
	v_div_fixup_f32 v21, v21, v22, v23
	v_sub_f32_e32 v21, v21, v27
	v_bfe_u32 v22, v21, 16, 1
	s_mov_b32 s20, 16
	v_add3_u32 v21, v21, v22, s18
	s_mov_b64 s[16:17], 0
	s_and_b64 vcc, exec, s[4:5]
	ds_write_b16_d16_hi v20, v21 offset:7920
	s_cbranch_vccnz .LBB0_805
.LBB0_773:
	v_mov_b32_e32 v140, 0
	v_mov_b32_e32 v141, 0
	v_mov_b32_e32 v142, 0
	v_mov_b32_e32 v143, 0
	v_mov_b32_e32 v144, 0
	v_mov_b32_e32 v145, 0
	v_mov_b32_e32 v146, 0
	v_mov_b32_e32 v147, 0
	v_mov_b32_e32 v148, 0
	v_mov_b32_e32 v149, 0
	v_mov_b32_e32 v150, 0
	v_mov_b32_e32 v151, 0
	v_mov_b32_e32 v152, 0
	v_mov_b32_e32 v153, 0
	v_mov_b32_e32 v154, 0
	v_mov_b32_e32 v155, 0
	s_mul_i32 s6, s20, 0x700
	v_lshl_add_u64 v[20:21], s[6:7], 1, v[18:19]
	global_load_ushort v73, v[20:21], off
	v_or_b32_e32 v22, s20, v1
	v_cmp_ge_u32_e32 vcc, v22, v28
	v_mov_b32_e32 v52, 0
	v_mov_b32_e32 v77, 0
	s_and_saveexec_b64 s[4:5], vcc
	s_cbranch_execz .LBB0_775
	v_sub_u32_e32 v24, s20, v28
	v_mul_i32_i24_e32 v24, 0x700, v24
	v_ashrrev_i32_e32 v25, 31, v24
	v_lshl_add_u64 v[24:25], v[24:25], 1, v[18:19]
	global_load_ushort v140, v[24:25], off
.LBB0_775:
	s_or_b64 exec, exec, s[4:5]
	global_load_ushort v69, v[20:21], off offset:3584
	v_or_b32_e32 v81, 1, v22
	v_cmp_ge_u32_e32 vcc, v81, v28
	s_and_saveexec_b64 s[4:5], vcc
	s_cbranch_execz .LBB0_777
	s_or_b32 s21, s20, 1
	v_sub_u32_e32 v24, s21, v28
	v_mul_i32_i24_e32 v24, 0x700, v24
	v_ashrrev_i32_e32 v25, 31, v24
	v_lshl_add_u64 v[24:25], v[24:25], 1, v[18:19]
	global_load_ushort v141, v[24:25], off
.LBB0_777:
	s_or_b64 exec, exec, s[4:5]
	v_lshl_add_u64 v[20:21], v[20:21], 0, s[12:13]
	global_load_ushort v65, v[20:21], off offset:3584
	v_or_b32_e32 v80, 2, v22
	v_cmp_ge_u32_e32 vcc, v80, v28
	v_mov_b32_e32 v44, 0
	v_mov_b32_e32 v72, 0
	s_and_saveexec_b64 s[4:5], vcc
	s_cbranch_execz .LBB0_779
	s_or_b32 s21, s20, 2
	v_sub_u32_e32 v24, s21, v28
	v_mul_i32_i24_e32 v24, 0x700, v24
	v_ashrrev_i32_e32 v25, 31, v24
	v_lshl_add_u64 v[24:25], v[24:25], 1, v[18:19]
	global_load_ushort v142, v[24:25], off
.LBB0_779:
	s_or_b64 exec, exec, s[4:5]
	v_lshl_add_u64 v[20:21], v[20:21], 0, s[12:13]
	global_load_ushort v60, v[20:21], off offset:3584
	v_or_b32_e32 v79, 3, v22
	v_cmp_ge_u32_e32 vcc, v79, v28
	s_and_saveexec_b64 s[4:5], vcc
	s_cbranch_execz .LBB0_781
	s_or_b32 s21, s20, 3
	v_sub_u32_e32 v20, s21, v28
	v_mul_i32_i24_e32 v20, 0x700, v20
	v_ashrrev_i32_e32 v21, 31, v20
	v_lshl_add_u64 v[20:21], v[20:21], 1, v[18:19]
	global_load_ushort v143, v[20:21], off
.LBB0_781:
	s_or_b64 exec, exec, s[4:5]
	s_addk_i32 s6, 0x1c00
	v_lshl_add_u64 v[20:21], s[6:7], 1, v[18:19]
	global_load_ushort v57, v[20:21], off
	v_or_b32_e32 v78, 4, v22
	v_cmp_ge_u32_e32 vcc, v78, v28
	v_mov_b32_e32 v37, 0
	v_mov_b32_e32 v63, 0
	s_and_saveexec_b64 s[4:5], vcc
	s_cbranch_execz .LBB0_783
	s_or_b32 s21, s20, 4
	v_sub_u32_e32 v20, s21, v28
	v_mul_i32_i24_e32 v20, 0x700, v20
	v_ashrrev_i32_e32 v21, 31, v20
	v_lshl_add_u64 v[20:21], v[20:21], 1, v[18:19]
	global_load_ushort v144, v[20:21], off
.LBB0_783:
	s_or_b64 exec, exec, s[4:5]
	s_addk_i32 s6, 0x700
	v_lshl_add_u64 v[20:21], s[6:7], 1, v[18:19]
	global_load_ushort v55, v[20:21], off
	v_or_b32_e32 v76, 5, v22
	v_cmp_ge_u32_e32 vcc, v76, v28
	s_and_saveexec_b64 s[4:5], vcc
	s_cbranch_execz .LBB0_785
	s_or_b32 s21, s20, 5
	v_sub_u32_e32 v20, s21, v28
	v_mul_i32_i24_e32 v20, 0x700, v20
	v_ashrrev_i32_e32 v21, 31, v20
	v_lshl_add_u64 v[20:21], v[20:21], 1, v[18:19]
	global_load_ushort v145, v[20:21], off
.LBB0_785:
	s_or_b64 exec, exec, s[4:5]
	s_addk_i32 s6, 0x700
	v_lshl_add_u64 v[20:21], s[6:7], 1, v[18:19]
	global_load_ushort v51, v[20:21], off
	v_or_b32_e32 v75, 6, v22
	v_cmp_ge_u32_e32 vcc, v75, v28
	v_mov_b32_e32 v34, 0
	v_mov_b32_e32 v59, 0
	s_and_saveexec_b64 s[4:5], vcc
	s_cbranch_execz .LBB0_787
	s_or_b32 s21, s20, 6
	v_sub_u32_e32 v20, s21, v28
	v_mul_i32_i24_e32 v20, 0x700, v20
	v_ashrrev_i32_e32 v21, 31, v20
	v_lshl_add_u64 v[20:21], v[20:21], 1, v[18:19]
	global_load_ushort v146, v[20:21], off
.LBB0_787:
	s_or_b64 exec, exec, s[4:5]
	s_addk_i32 s6, 0x700
	v_lshl_add_u64 v[20:21], s[6:7], 1, v[18:19]
	global_load_ushort v50, v[20:21], off
	v_or_b32_e32 v74, 7, v22
	v_cmp_ge_u32_e32 vcc, v74, v28
	s_and_saveexec_b64 s[4:5], vcc
	s_cbranch_execz .LBB0_789
	s_or_b32 s21, s20, 7
	v_sub_u32_e32 v20, s21, v28
	v_mul_i32_i24_e32 v20, 0x700, v20
	v_ashrrev_i32_e32 v21, 31, v20
	v_lshl_add_u64 v[20:21], v[20:21], 1, v[18:19]
	global_load_ushort v147, v[20:21], off
.LBB0_789:
	s_or_b64 exec, exec, s[4:5]
	s_addk_i32 s6, 0x700
	v_lshl_add_u64 v[20:21], s[6:7], 1, v[18:19]
	global_load_ushort v48, v[20:21], off
	v_or_b32_e32 v71, 8, v22
	v_cmp_ge_u32_e32 vcc, v71, v28
	v_mov_b32_e32 v27, 0
	v_mov_b32_e32 v54, 0
	s_and_saveexec_b64 s[4:5], vcc
	s_cbranch_execz .LBB0_791
	s_or_b32 s21, s20, 8
	v_sub_u32_e32 v20, s21, v28
	v_mul_i32_i24_e32 v20, 0x700, v20
	v_ashrrev_i32_e32 v21, 31, v20
	v_lshl_add_u64 v[20:21], v[20:21], 1, v[18:19]
	global_load_ushort v148, v[20:21], off
.LBB0_791:
	s_or_b64 exec, exec, s[4:5]
	s_addk_i32 s6, 0x700
	v_lshl_add_u64 v[20:21], s[6:7], 1, v[18:19]
	global_load_ushort v47, v[20:21], off
	v_or_b32_e32 v70, 9, v22
	v_cmp_ge_u32_e32 vcc, v70, v28
	s_and_saveexec_b64 s[4:5], vcc
	s_cbranch_execz .LBB0_793
	s_or_b32 s21, s20, 9
	v_sub_u32_e32 v20, s21, v28
	v_mul_i32_i24_e32 v20, 0x700, v20
	v_ashrrev_i32_e32 v21, 31, v20
	v_lshl_add_u64 v[20:21], v[20:21], 1, v[18:19]
	global_load_ushort v149, v[20:21], off
.LBB0_793:
	s_or_b64 exec, exec, s[4:5]
	s_addk_i32 s6, 0x700
	v_lshl_add_u64 v[20:21], s[6:7], 1, v[18:19]
	global_load_ushort v45, v[20:21], off
	v_or_b32_e32 v68, 10, v22
	v_cmp_ge_u32_e32 vcc, v68, v28
	v_mov_b32_e32 v26, 0
	v_mov_b32_e32 v49, 0
	s_and_saveexec_b64 s[4:5], vcc
	s_cbranch_execz .LBB0_795
	s_or_b32 s21, s20, 10
	v_sub_u32_e32 v20, s21, v28
	v_mul_i32_i24_e32 v20, 0x700, v20
	v_ashrrev_i32_e32 v21, 31, v20
	v_lshl_add_u64 v[20:21], v[20:21], 1, v[18:19]
	global_load_ushort v150, v[20:21], off
.LBB0_795:
	s_or_b64 exec, exec, s[4:5]
	s_addk_i32 s6, 0x700
	v_lshl_add_u64 v[20:21], s[6:7], 1, v[18:19]
	global_load_ushort v43, v[20:21], off
	v_or_b32_e32 v62, 11, v22
	v_cmp_ge_u32_e32 vcc, v62, v28
	s_and_saveexec_b64 s[4:5], vcc
	s_cbranch_execz .LBB0_797
	s_or_b32 s21, s20, 11
	v_sub_u32_e32 v20, s21, v28
	v_mul_i32_i24_e32 v20, 0x700, v20
	v_ashrrev_i32_e32 v21, 31, v20
	v_lshl_add_u64 v[20:21], v[20:21], 1, v[18:19]
	global_load_ushort v151, v[20:21], off
.LBB0_797:
	s_or_b64 exec, exec, s[4:5]
	s_addk_i32 s6, 0x700
	v_lshl_add_u64 v[20:21], s[6:7], 1, v[18:19]
	global_load_ushort v41, v[20:21], off
	v_or_b32_e32 v61, 12, v22
	v_cmp_ge_u32_e32 vcc, v61, v28
	v_mov_b32_e32 v25, 0
	v_mov_b32_e32 v46, 0
	s_and_saveexec_b64 s[4:5], vcc
	s_cbranch_execz .LBB0_799
	s_or_b32 s21, s20, 12
	v_sub_u32_e32 v20, s21, v28
	v_mul_i32_i24_e32 v20, 0x700, v20
	v_ashrrev_i32_e32 v21, 31, v20
	v_lshl_add_u64 v[20:21], v[20:21], 1, v[18:19]
	global_load_ushort v152, v[20:21], off
.LBB0_799:
	s_or_b64 exec, exec, s[4:5]
	s_addk_i32 s6, 0x700
	v_lshl_add_u64 v[20:21], s[6:7], 1, v[18:19]
	global_load_ushort v40, v[20:21], off
	v_or_b32_e32 v58, 13, v22
	v_cmp_ge_u32_e32 vcc, v58, v28
	s_and_saveexec_b64 s[4:5], vcc
	s_cbranch_execz .LBB0_801
	s_or_b32 s21, s20, 13
	v_sub_u32_e32 v20, s21, v28
	v_mul_i32_i24_e32 v20, 0x700, v20
	v_ashrrev_i32_e32 v21, 31, v20
	v_lshl_add_u64 v[20:21], v[20:21], 1, v[18:19]
	global_load_ushort v153, v[20:21], off
.LBB0_801:
	s_or_b64 exec, exec, s[4:5]
	s_addk_i32 s6, 0x700
	v_lshl_add_u64 v[20:21], s[6:7], 1, v[18:19]
	global_load_ushort v36, v[20:21], off
	v_or_b32_e32 v56, 14, v22
	v_cmp_ge_u32_e32 vcc, v56, v28
	v_mov_b32_e32 v24, 0
	v_mov_b32_e32 v42, 0
	s_and_saveexec_b64 s[4:5], vcc
	s_cbranch_execz .LBB0_803
	s_or_b32 s21, s20, 14
	v_sub_u32_e32 v20, s21, v28
	v_mul_i32_i24_e32 v20, 0x700, v20
	v_ashrrev_i32_e32 v21, 31, v20
	v_lshl_add_u64 v[20:21], v[20:21], 1, v[18:19]
	global_load_ushort v154, v[20:21], off
.LBB0_803:
	s_or_b64 exec, exec, s[4:5]
	s_addk_i32 s6, 0x700
	v_lshl_add_u64 v[20:21], s[6:7], 1, v[18:19]
	global_load_ushort v35, v[20:21], off
	v_or_b32_e32 v53, 15, v22
	v_cmp_ge_u32_e32 vcc, v53, v28
	s_and_saveexec_b64 s[4:5], vcc
	s_cbranch_execz .LBB0_772
	s_or_b32 s6, s20, 15
	v_sub_u32_e32 v20, s6, v28
	v_mul_i32_i24_e32 v20, 0x700, v20
	v_ashrrev_i32_e32 v21, 31, v20
	v_lshl_add_u64 v[20:21], v[20:21], 1, v[18:19]
	global_load_ushort v155, v[20:21], off
	s_branch .LBB0_772

.LBB0_2481:
	s_or_b64 exec, exec, s[4:5]
	s_waitcnt vmcnt(0)
	v_cvt_f32_f16_e32 v81, v140
	v_cvt_f32_f16_e32 v56, v141
	v_cvt_f32_f16_e32 v76, v142
	v_cvt_f32_f16_e32 v48, v143
	v_cvt_f32_f16_e32 v70, v144
	v_cvt_f32_f16_e32 v43, v145
	v_cvt_f32_f16_e32 v63, v146
	v_cvt_f32_f16_e32 v40, v147
	v_cvt_f32_f16_e32 v58, v148
	v_cvt_f32_f16_e32 v31, v149
	v_cvt_f32_f16_e32 v53, v150
	v_cvt_f32_f16_e32 v30, v151
	v_cvt_f32_f16_e32 v50, v152
	v_cvt_f32_f16_e32 v29, v153
	v_cvt_f32_f16_e32 v46, v154
	v_cvt_f32_f16_e32 v28, v155
	s_waitcnt vmcnt(15)
	v_cvt_f32_f16_e32 v24, v77
	v_min_u32_e32 v25, v85, v32
	v_cvt_f32_ubyte0_e32 v25, v25
	s_waitcnt vmcnt(14)
	v_cvt_f32_f16_e32 v73, v73
	v_add_f32_e32 v27, v27, v24
	v_sub_f32_e32 v27, v27, v81
	v_div_scale_f32 v77, s[4:5], v25, v25, v27
	v_rcp_f32_e32 v81, v77
	s_xor_b64 s[4:5], s[16:17], -1
	v_or_b32_e32 v85, s20, v21
	s_waitcnt vmcnt(13)
	v_cvt_f32_f16_e32 v71, v71
	v_fma_f32 v86, -v77, v81, 1.0
	v_fmac_f32_e32 v81, v86, v81
	v_div_scale_f32 v86, vcc, v27, v25, v27
	v_mul_f32_e32 v87, v86, v81
	v_fma_f32 v88, -v77, v87, v86
	v_fmac_f32_e32 v87, v88, v81
	v_fma_f32 v77, -v77, v87, v86
	v_div_fmas_f32 v77, v77, v81, v87
	v_div_fixup_f32 v25, v77, v25, v27
	v_sub_f32_e32 v24, v25, v24
	v_bfe_u32 v25, v24, 16, 1
	v_add3_u32 v77, v24, v25, s18
	v_add_f32_e32 v24, v27, v73
	v_sub_f32_e32 v27, v24, v56
	v_min_u32_e32 v24, v84, v32
	v_cvt_f32_ubyte0_e32 v56, v24
	v_div_scale_f32 v81, s[16:17], v56, v56, v27
	v_rcp_f32_e32 v84, v81
	v_mad_u64_u32 v[24:25], s[16:17], v85, s0, v[0:1]
	ds_write_b16_d16_hi v24, v77
	v_fma_f32 v25, -v81, v84, 1.0
	v_fmac_f32_e32 v84, v25, v84
	v_div_scale_f32 v25, vcc, v27, v56, v27
	v_mul_f32_e32 v77, v25, v84
	v_fma_f32 v85, -v81, v77, v25
	v_fmac_f32_e32 v77, v85, v84
	v_fma_f32 v25, -v81, v77, v25
	v_div_fmas_f32 v25, v25, v84, v77
	v_div_fixup_f32 v25, v25, v56, v27
	v_add_f32_e32 v27, v27, v71
	v_min_u32_e32 v56, v83, v32
	v_sub_f32_e32 v27, v27, v76
	v_cvt_f32_ubyte0_e32 v56, v56
	v_sub_f32_e32 v25, v25, v73
	v_div_scale_f32 v73, s[16:17], v56, v56, v27
	v_rcp_f32_e32 v76, v73
	v_bfe_u32 v77, v25, 16, 1
	v_add3_u32 v25, v25, v77, s18
	ds_write_b16_d16_hi v24, v25 offset:528
	v_fma_f32 v25, -v73, v76, 1.0
	v_fmac_f32_e32 v76, v25, v76
	v_div_scale_f32 v25, vcc, v27, v56, v27
	v_mul_f32_e32 v77, v25, v76
	v_fma_f32 v81, -v73, v77, v25
	s_waitcnt vmcnt(12)
	v_cvt_f32_f16_e32 v65, v65
	v_fmac_f32_e32 v77, v81, v76
	v_fma_f32 v25, -v73, v77, v25
	v_div_fmas_f32 v25, v25, v76, v77
	v_div_fixup_f32 v25, v25, v56, v27
	v_add_f32_e32 v27, v27, v65
	v_sub_f32_e32 v27, v27, v48
	v_min_u32_e32 v48, v82, v32
	v_cvt_f32_ubyte0_e32 v48, v48
	v_div_scale_f32 v56, s[16:17], v48, v48, v27
	v_sub_f32_e32 v25, v25, v71
	v_rcp_f32_e32 v71, v56
	v_bfe_u32 v73, v25, 16, 1
	v_add3_u32 v25, v25, v73, s18
	ds_write_b16_d16_hi v24, v25 offset:1056
	v_fma_f32 v25, -v56, v71, 1.0
	v_fmac_f32_e32 v71, v25, v71
	v_div_scale_f32 v25, vcc, v27, v48, v27
	v_mul_f32_e32 v73, v25, v71
	v_fma_f32 v76, -v56, v73, v25
	v_fmac_f32_e32 v73, v76, v71
	v_fma_f32 v25, -v56, v73, v25
	s_waitcnt vmcnt(11)
	v_cvt_f32_f16_e32 v56, v61
	v_div_fmas_f32 v25, v25, v71, v73
	v_div_fixup_f32 v25, v25, v48, v27
	v_min_u32_e32 v48, v80, v32
	v_add_f32_e32 v27, v27, v56
	v_sub_f32_e32 v27, v27, v70
	v_cvt_f32_ubyte0_e32 v48, v48
	v_div_scale_f32 v61, s[16:17], v48, v48, v27
	v_sub_f32_e32 v25, v25, v65
	v_rcp_f32_e32 v65, v61
	v_bfe_u32 v70, v25, 16, 1
	v_add3_u32 v25, v25, v70, s18
	ds_write_b16_d16_hi v24, v25 offset:1584
	v_fma_f32 v25, -v61, v65, 1.0
	v_fmac_f32_e32 v65, v25, v65
	v_div_scale_f32 v25, vcc, v27, v48, v27
	v_mul_f32_e32 v70, v25, v65
	v_fma_f32 v71, -v61, v70, v25
	s_waitcnt vmcnt(10)
	v_cvt_f32_f16_e32 v59, v59
	v_fmac_f32_e32 v70, v71, v65
	v_fma_f32 v25, -v61, v70, v25
	v_div_fmas_f32 v25, v25, v65, v70
	v_div_fixup_f32 v25, v25, v48, v27
	v_add_f32_e32 v27, v27, v59
	v_sub_f32_e32 v27, v27, v43
	v_min_u32_e32 v43, v79, v32
	v_cvt_f32_ubyte0_e32 v43, v43
	v_div_scale_f32 v48, s[16:17], v43, v43, v27
	v_sub_f32_e32 v25, v25, v56
	v_rcp_f32_e32 v56, v48
	v_bfe_u32 v61, v25, 16, 1
	v_add3_u32 v25, v25, v61, s18
	ds_write_b16_d16_hi v24, v25 offset:2112
	v_fma_f32 v25, -v48, v56, 1.0
	v_fmac_f32_e32 v56, v25, v56
	v_div_scale_f32 v25, vcc, v27, v43, v27
	v_mul_f32_e32 v61, v25, v56
	v_fma_f32 v65, -v48, v61, v25
	v_fmac_f32_e32 v61, v65, v56
	v_fma_f32 v25, -v48, v61, v25
	s_waitcnt vmcnt(9)
	v_cvt_f32_f16_e32 v48, v55
	v_div_fmas_f32 v25, v25, v56, v61
	v_div_fixup_f32 v25, v25, v43, v27
	v_min_u32_e32 v43, v78, v32
	v_add_f32_e32 v27, v27, v48
	v_sub_f32_e32 v27, v27, v63
	v_cvt_f32_ubyte0_e32 v43, v43
	v_div_scale_f32 v55, s[16:17], v43, v43, v27
	v_rcp_f32_e32 v56, v55
	v_sub_f32_e32 v25, v25, v59
	v_bfe_u32 v59, v25, 16, 1
	v_add3_u32 v25, v25, v59, s18
	ds_write_b16_d16_hi v24, v25 offset:2640
	v_fma_f32 v25, -v55, v56, 1.0
	v_fmac_f32_e32 v56, v25, v56
	v_div_scale_f32 v25, vcc, v27, v43, v27
	v_mul_f32_e32 v59, v25, v56
	v_fma_f32 v61, -v55, v59, v25
	s_waitcnt vmcnt(8)
	v_cvt_f32_f16_e32 v54, v54
	v_fmac_f32_e32 v59, v61, v56
	v_fma_f32 v25, -v55, v59, v25
	v_div_fmas_f32 v25, v25, v56, v59
	v_div_fixup_f32 v25, v25, v43, v27
	v_add_f32_e32 v27, v27, v54
	v_sub_f32_e32 v27, v27, v40
	v_min_u32_e32 v40, v75, v32
	v_cvt_f32_ubyte0_e32 v40, v40
	v_div_scale_f32 v43, s[16:17], v40, v40, v27
	v_sub_f32_e32 v25, v25, v48
	v_rcp_f32_e32 v48, v43
	v_bfe_u32 v55, v25, 16, 1
	v_add3_u32 v25, v25, v55, s18
	ds_write_b16_d16_hi v24, v25 offset:3168
	v_fma_f32 v25, -v43, v48, 1.0
	v_fmac_f32_e32 v48, v25, v48
	v_div_scale_f32 v25, vcc, v27, v40, v27
	v_mul_f32_e32 v55, v25, v48
	v_fma_f32 v56, -v43, v55, v25
	v_fmac_f32_e32 v55, v56, v48
	v_fma_f32 v25, -v43, v55, v25
	s_waitcnt vmcnt(7)
	v_cvt_f32_f16_e32 v43, v52
	v_div_fmas_f32 v25, v25, v48, v55
	v_div_fixup_f32 v25, v25, v40, v27
	v_min_u32_e32 v40, v74, v32
	v_add_f32_e32 v27, v27, v43
	v_sub_f32_e32 v27, v27, v58
	v_cvt_f32_ubyte0_e32 v40, v40
	v_div_scale_f32 v48, s[16:17], v40, v40, v27
	v_rcp_f32_e32 v52, v48
	v_sub_f32_e32 v25, v25, v54
	v_bfe_u32 v54, v25, 16, 1
	v_add3_u32 v25, v25, v54, s18
	ds_write_b16_d16_hi v24, v25 offset:3696
	v_fma_f32 v25, -v48, v52, 1.0
	v_fmac_f32_e32 v52, v25, v52
	v_div_scale_f32 v25, vcc, v27, v40, v27
	v_mul_f32_e32 v54, v25, v52
	v_fma_f32 v55, -v48, v54, v25
	v_fmac_f32_e32 v54, v55, v52
	v_fma_f32 v25, -v48, v54, v25
	s_waitcnt vmcnt(6)
	v_cvt_f32_f16_e32 v48, v51
	v_div_fmas_f32 v25, v25, v52, v54
	v_div_fixup_f32 v25, v25, v40, v27
	v_sub_f32_e32 v25, v25, v43
	v_add_f32_e32 v27, v27, v48
	v_sub_f32_e32 v27, v27, v31
	v_min_u32_e32 v31, v72, v32
	v_cvt_f32_ubyte0_e32 v31, v31
	v_div_scale_f32 v40, s[16:17], v31, v31, v27
	v_rcp_f32_e32 v43, v40
	v_bfe_u32 v51, v25, 16, 1
	v_add3_u32 v25, v25, v51, s18
	ds_write_b16_d16_hi v24, v25 offset:4224
	v_fma_f32 v25, -v40, v43, 1.0
	v_fmac_f32_e32 v43, v25, v43
	v_div_scale_f32 v25, vcc, v27, v31, v27
	v_mul_f32_e32 v51, v25, v43
	v_fma_f32 v52, -v40, v51, v25
	v_fmac_f32_e32 v51, v52, v43
	v_fma_f32 v25, -v40, v51, v25
	s_waitcnt vmcnt(5)
	v_cvt_f32_f16_e32 v40, v49
	v_div_fmas_f32 v25, v25, v43, v51
	v_div_fixup_f32 v25, v25, v31, v27
	v_min_u32_e32 v31, v69, v32
	v_add_f32_e32 v27, v27, v40
	v_sub_f32_e32 v27, v27, v53
	v_cvt_f32_ubyte0_e32 v31, v31
	v_div_scale_f32 v43, s[16:17], v31, v31, v27
	v_sub_f32_e32 v25, v25, v48
	v_rcp_f32_e32 v48, v43
	v_bfe_u32 v49, v25, 16, 1
	v_add3_u32 v25, v25, v49, s18
	ds_write_b16_d16_hi v24, v25 offset:4752
	v_fma_f32 v25, -v43, v48, 1.0
	v_fmac_f32_e32 v48, v25, v48
	v_div_scale_f32 v25, vcc, v27, v31, v27
	v_mul_f32_e32 v49, v25, v48
	v_fma_f32 v51, -v43, v49, v25
	v_fmac_f32_e32 v49, v51, v48
	v_fma_f32 v25, -v43, v49, v25
	s_waitcnt vmcnt(4)
	v_cvt_f32_f16_e32 v43, v47
	v_div_fmas_f32 v25, v25, v48, v49
	v_div_fixup_f32 v25, v25, v31, v27
	v_sub_f32_e32 v25, v25, v40
	v_add_f32_e32 v27, v27, v43
	v_sub_f32_e32 v27, v27, v30
	v_min_u32_e32 v30, v68, v32
	v_cvt_f32_ubyte0_e32 v30, v30
	v_div_scale_f32 v31, s[16:17], v30, v30, v27
	v_rcp_f32_e32 v40, v31
	v_bfe_u32 v47, v25, 16, 1
	v_add3_u32 v25, v25, v47, s18
	ds_write_b16_d16_hi v24, v25 offset:5280
	v_fma_f32 v25, -v31, v40, 1.0
	v_fmac_f32_e32 v40, v25, v40
	v_div_scale_f32 v25, vcc, v27, v30, v27
	v_mul_f32_e32 v47, v25, v40
	v_fma_f32 v48, -v31, v47, v25
	v_fmac_f32_e32 v47, v48, v40
	v_fma_f32 v25, -v31, v47, v25
	s_waitcnt vmcnt(3)
	v_cvt_f32_f16_e32 v31, v45
	v_div_fmas_f32 v25, v25, v40, v47
	v_div_fixup_f32 v25, v25, v30, v27
	v_min_u32_e32 v30, v62, v32
	v_add_f32_e32 v27, v27, v31
	v_sub_f32_e32 v27, v27, v50
	v_cvt_f32_ubyte0_e32 v30, v30
	v_div_scale_f32 v40, s[16:17], v30, v30, v27
	v_sub_f32_e32 v25, v25, v43
	v_rcp_f32_e32 v43, v40
	v_bfe_u32 v45, v25, 16, 1
	v_add3_u32 v25, v25, v45, s18
	ds_write_b16_d16_hi v24, v25 offset:5808
	v_fma_f32 v25, -v40, v43, 1.0
	v_fmac_f32_e32 v43, v25, v43
	v_div_scale_f32 v25, vcc, v27, v30, v27
	v_mul_f32_e32 v45, v25, v43
	v_fma_f32 v47, -v40, v45, v25
	v_fmac_f32_e32 v45, v47, v43
	v_fma_f32 v25, -v40, v45, v25
	s_waitcnt vmcnt(2)
	v_cvt_f32_f16_e32 v40, v44
	v_div_fmas_f32 v25, v25, v43, v45
	v_div_fixup_f32 v25, v25, v30, v27
	v_sub_f32_e32 v25, v25, v31
	v_add_f32_e32 v27, v27, v40
	v_sub_f32_e32 v27, v27, v29
	v_min_u32_e32 v29, v60, v32
	v_cvt_f32_ubyte0_e32 v29, v29
	v_div_scale_f32 v30, s[16:17], v29, v29, v27
	v_rcp_f32_e32 v31, v30
	v_bfe_u32 v43, v25, 16, 1
	v_add3_u32 v25, v25, v43, s18
	ds_write_b16_d16_hi v24, v25 offset:6336
	v_fma_f32 v25, -v30, v31, 1.0
	v_fmac_f32_e32 v31, v25, v31
	v_div_scale_f32 v25, vcc, v27, v29, v27
	v_mul_f32_e32 v43, v25, v31
	v_fma_f32 v44, -v30, v43, v25
	v_fmac_f32_e32 v43, v44, v31
	v_fma_f32 v25, -v30, v43, v25
	s_waitcnt vmcnt(1)
	v_cvt_f32_f16_e32 v30, v42
	v_div_fmas_f32 v25, v25, v31, v43
	v_div_fixup_f32 v25, v25, v29, v27
	v_min_u32_e32 v29, v57, v32
	v_add_f32_e32 v27, v27, v30
	v_sub_f32_e32 v27, v27, v46
	v_cvt_f32_ubyte0_e32 v29, v29
	v_div_scale_f32 v31, s[16:17], v29, v29, v27
	v_sub_f32_e32 v25, v25, v40
	v_rcp_f32_e32 v40, v31
	v_bfe_u32 v42, v25, 16, 1
	v_add3_u32 v25, v25, v42, s18
	ds_write_b16_d16_hi v24, v25 offset:6864
	v_fma_f32 v25, -v31, v40, 1.0
	v_fmac_f32_e32 v40, v25, v40
	v_div_scale_f32 v25, vcc, v27, v29, v27
	v_mul_f32_e32 v42, v25, v40
	v_fma_f32 v43, -v31, v42, v25
	v_fmac_f32_e32 v42, v43, v40
	v_fma_f32 v25, -v31, v42, v25
	s_waitcnt vmcnt(0)
	v_cvt_f32_f16_e32 v31, v41
	v_div_fmas_f32 v25, v25, v40, v42
	v_add_u32_e32 v26, 16, v26
	v_div_fixup_f32 v25, v25, v29, v27
	v_add_f32_e32 v27, v27, v31
	v_min_u32_e32 v26, v26, v32
	v_sub_f32_e32 v27, v27, v28
	v_cvt_f32_ubyte0_e32 v26, v26
	v_div_scale_f32 v28, s[16:17], v26, v26, v27
	v_sub_f32_e32 v25, v25, v30
	v_rcp_f32_e32 v30, v28
	v_bfe_u32 v29, v25, 16, 1
	v_add3_u32 v25, v25, v29, s18
	ds_write_b16_d16_hi v24, v25 offset:7392
	v_fma_f32 v25, -v28, v30, 1.0
	v_fmac_f32_e32 v30, v25, v30
	v_div_scale_f32 v25, vcc, v27, v26, v27
	v_mul_f32_e32 v29, v25, v30
	v_fma_f32 v40, -v28, v29, v25
	v_fmac_f32_e32 v29, v40, v30
	v_fma_f32 v25, -v28, v29, v25
	v_div_fmas_f32 v25, v25, v30, v29
	v_div_fixup_f32 v25, v25, v26, v27
	v_sub_f32_e32 v25, v25, v31
	v_bfe_u32 v26, v25, 16, 1
	s_mov_b32 s20, 16
	v_add3_u32 v25, v25, v26, s18
	s_mov_b64 s[16:17], 0
	s_and_b64 vcc, exec, s[4:5]
	ds_write_b16_d16_hi v24, v25 offset:7920
	s_cbranch_vccnz .LBB0_2514
.LBB0_2482:
	v_mov_b32_e32 v140, 0
	v_mov_b32_e32 v141, 0
	v_mov_b32_e32 v142, 0
	v_mov_b32_e32 v143, 0
	v_mov_b32_e32 v144, 0
	v_mov_b32_e32 v145, 0
	v_mov_b32_e32 v146, 0
	v_mov_b32_e32 v147, 0
	v_mov_b32_e32 v148, 0
	v_mov_b32_e32 v149, 0
	v_mov_b32_e32 v150, 0
	v_mov_b32_e32 v151, 0
	v_mov_b32_e32 v152, 0
	v_mov_b32_e32 v153, 0
	v_mov_b32_e32 v154, 0
	v_mov_b32_e32 v155, 0
	s_mul_i32 s6, s20, 0x700
	v_lshl_add_u64 v[24:25], s[6:7], 1, v[22:23]
	global_load_ushort v77, v[24:25], off
	v_or_b32_e32 v26, s20, v1
	v_cmp_ge_u32_e32 vcc, v26, v32
	v_mov_b32_e32 v56, 0
	v_mov_b32_e32 v81, 0
	s_and_saveexec_b64 s[4:5], vcc
	s_cbranch_execz .LBB0_2484
	v_sub_u32_e32 v28, s20, v32
	v_mul_i32_i24_e32 v28, 0x700, v28
	v_ashrrev_i32_e32 v29, 31, v28
	v_lshl_add_u64 v[28:29], v[28:29], 1, v[22:23]
	global_load_ushort v140, v[28:29], off
.LBB0_2484:
	s_or_b64 exec, exec, s[4:5]
	global_load_ushort v73, v[24:25], off offset:3584
	v_or_b32_e32 v85, 1, v26
	v_cmp_ge_u32_e32 vcc, v85, v32
	s_and_saveexec_b64 s[4:5], vcc
	s_cbranch_execz .LBB0_2486
	s_or_b32 s21, s20, 1
	v_sub_u32_e32 v28, s21, v32
	v_mul_i32_i24_e32 v28, 0x700, v28
	v_ashrrev_i32_e32 v29, 31, v28
	v_lshl_add_u64 v[28:29], v[28:29], 1, v[22:23]
	global_load_ushort v141, v[28:29], off
.LBB0_2486:
	s_or_b64 exec, exec, s[4:5]
	v_lshl_add_u64 v[24:25], v[24:25], 0, s[12:13]
	global_load_ushort v71, v[24:25], off offset:3584
	v_or_b32_e32 v84, 2, v26
	v_cmp_ge_u32_e32 vcc, v84, v32
	v_mov_b32_e32 v48, 0
	v_mov_b32_e32 v76, 0
	s_and_saveexec_b64 s[4:5], vcc
	s_cbranch_execz .LBB0_2488
	s_or_b32 s21, s20, 2
	v_sub_u32_e32 v28, s21, v32
	v_mul_i32_i24_e32 v28, 0x700, v28
	v_ashrrev_i32_e32 v29, 31, v28
	v_lshl_add_u64 v[28:29], v[28:29], 1, v[22:23]
	global_load_ushort v142, v[28:29], off
.LBB0_2488:
	s_or_b64 exec, exec, s[4:5]
	v_lshl_add_u64 v[24:25], v[24:25], 0, s[12:13]
	global_load_ushort v65, v[24:25], off offset:3584
	v_or_b32_e32 v83, 3, v26
	v_cmp_ge_u32_e32 vcc, v83, v32
	s_and_saveexec_b64 s[4:5], vcc
	s_cbranch_execz .LBB0_2490
	s_or_b32 s21, s20, 3
	v_sub_u32_e32 v24, s21, v32
	v_mul_i32_i24_e32 v24, 0x700, v24
	v_ashrrev_i32_e32 v25, 31, v24
	v_lshl_add_u64 v[24:25], v[24:25], 1, v[22:23]
	global_load_ushort v143, v[24:25], off
.LBB0_2490:
	s_or_b64 exec, exec, s[4:5]
	s_addk_i32 s6, 0x1c00
	v_lshl_add_u64 v[24:25], s[6:7], 1, v[22:23]
	global_load_ushort v61, v[24:25], off
	v_or_b32_e32 v82, 4, v26
	v_cmp_ge_u32_e32 vcc, v82, v32
	v_mov_b32_e32 v43, 0
	v_mov_b32_e32 v70, 0
	s_and_saveexec_b64 s[4:5], vcc
	s_cbranch_execz .LBB0_2492
	s_or_b32 s21, s20, 4
	v_sub_u32_e32 v24, s21, v32
	v_mul_i32_i24_e32 v24, 0x700, v24
	v_ashrrev_i32_e32 v25, 31, v24
	v_lshl_add_u64 v[24:25], v[24:25], 1, v[22:23]
	global_load_ushort v144, v[24:25], off
.LBB0_2492:
	s_or_b64 exec, exec, s[4:5]
	s_addk_i32 s6, 0x700
	v_lshl_add_u64 v[24:25], s[6:7], 1, v[22:23]
	global_load_ushort v59, v[24:25], off
	v_or_b32_e32 v80, 5, v26
	v_cmp_ge_u32_e32 vcc, v80, v32
	s_and_saveexec_b64 s[4:5], vcc
	s_cbranch_execz .LBB0_2494
	s_or_b32 s21, s20, 5
	v_sub_u32_e32 v24, s21, v32
	v_mul_i32_i24_e32 v24, 0x700, v24
	v_ashrrev_i32_e32 v25, 31, v24
	v_lshl_add_u64 v[24:25], v[24:25], 1, v[22:23]
	global_load_ushort v145, v[24:25], off
.LBB0_2494:
	s_or_b64 exec, exec, s[4:5]
	s_addk_i32 s6, 0x700
	v_lshl_add_u64 v[24:25], s[6:7], 1, v[22:23]
	global_load_ushort v55, v[24:25], off
	v_or_b32_e32 v79, 6, v26
	v_cmp_ge_u32_e32 vcc, v79, v32
	v_mov_b32_e32 v40, 0
	v_mov_b32_e32 v63, 0
	s_and_saveexec_b64 s[4:5], vcc
	s_cbranch_execz .LBB0_2496
	s_or_b32 s21, s20, 6
	v_sub_u32_e32 v24, s21, v32
	v_mul_i32_i24_e32 v24, 0x700, v24
	v_ashrrev_i32_e32 v25, 31, v24
	v_lshl_add_u64 v[24:25], v[24:25], 1, v[22:23]
	global_load_ushort v146, v[24:25], off
.LBB0_2496:
	s_or_b64 exec, exec, s[4:5]
	s_addk_i32 s6, 0x700
	v_lshl_add_u64 v[24:25], s[6:7], 1, v[22:23]
	global_load_ushort v54, v[24:25], off
	v_or_b32_e32 v78, 7, v26
	v_cmp_ge_u32_e32 vcc, v78, v32
	s_and_saveexec_b64 s[4:5], vcc
	s_cbranch_execz .LBB0_2498
	s_or_b32 s21, s20, 7
	v_sub_u32_e32 v24, s21, v32
	v_mul_i32_i24_e32 v24, 0x700, v24
	v_ashrrev_i32_e32 v25, 31, v24
	v_lshl_add_u64 v[24:25], v[24:25], 1, v[22:23]
	global_load_ushort v147, v[24:25], off
.LBB0_2498:
	s_or_b64 exec, exec, s[4:5]
	s_addk_i32 s6, 0x700
	v_lshl_add_u64 v[24:25], s[6:7], 1, v[22:23]
	global_load_ushort v52, v[24:25], off
	v_or_b32_e32 v75, 8, v26
	v_cmp_ge_u32_e32 vcc, v75, v32
	v_mov_b32_e32 v31, 0
	v_mov_b32_e32 v58, 0
	s_and_saveexec_b64 s[4:5], vcc
	s_cbranch_execz .LBB0_2500
	s_or_b32 s21, s20, 8
	v_sub_u32_e32 v24, s21, v32
	v_mul_i32_i24_e32 v24, 0x700, v24
	v_ashrrev_i32_e32 v25, 31, v24
	v_lshl_add_u64 v[24:25], v[24:25], 1, v[22:23]
	global_load_ushort v148, v[24:25], off
.LBB0_2500:
	s_or_b64 exec, exec, s[4:5]
	s_addk_i32 s6, 0x700
	v_lshl_add_u64 v[24:25], s[6:7], 1, v[22:23]
	global_load_ushort v51, v[24:25], off
	v_or_b32_e32 v74, 9, v26
	v_cmp_ge_u32_e32 vcc, v74, v32
	s_and_saveexec_b64 s[4:5], vcc
	s_cbranch_execz .LBB0_2502
	s_or_b32 s21, s20, 9
	v_sub_u32_e32 v24, s21, v32
	v_mul_i32_i24_e32 v24, 0x700, v24
	v_ashrrev_i32_e32 v25, 31, v24
	v_lshl_add_u64 v[24:25], v[24:25], 1, v[22:23]
	global_load_ushort v149, v[24:25], off
.LBB0_2502:
	s_or_b64 exec, exec, s[4:5]
	s_addk_i32 s6, 0x700
	v_lshl_add_u64 v[24:25], s[6:7], 1, v[22:23]
	global_load_ushort v49, v[24:25], off
	v_or_b32_e32 v72, 10, v26
	v_cmp_ge_u32_e32 vcc, v72, v32
	v_mov_b32_e32 v30, 0
	v_mov_b32_e32 v53, 0
	s_and_saveexec_b64 s[4:5], vcc
	s_cbranch_execz .LBB0_2504
	s_or_b32 s21, s20, 10
	v_sub_u32_e32 v24, s21, v32
	v_mul_i32_i24_e32 v24, 0x700, v24
	v_ashrrev_i32_e32 v25, 31, v24
	v_lshl_add_u64 v[24:25], v[24:25], 1, v[22:23]
	global_load_ushort v150, v[24:25], off
.LBB0_2504:
	s_or_b64 exec, exec, s[4:5]
	s_addk_i32 s6, 0x700
	v_lshl_add_u64 v[24:25], s[6:7], 1, v[22:23]
	global_load_ushort v47, v[24:25], off
	v_or_b32_e32 v69, 11, v26
	v_cmp_ge_u32_e32 vcc, v69, v32
	s_and_saveexec_b64 s[4:5], vcc
	s_cbranch_execz .LBB0_2506
	s_or_b32 s21, s20, 11
	v_sub_u32_e32 v24, s21, v32
	v_mul_i32_i24_e32 v24, 0x700, v24
	v_ashrrev_i32_e32 v25, 31, v24
	v_lshl_add_u64 v[24:25], v[24:25], 1, v[22:23]
	global_load_ushort v151, v[24:25], off
.LBB0_2506:
	s_or_b64 exec, exec, s[4:5]
	s_addk_i32 s6, 0x700
	v_lshl_add_u64 v[24:25], s[6:7], 1, v[22:23]
	global_load_ushort v45, v[24:25], off
	v_or_b32_e32 v68, 12, v26
	v_cmp_ge_u32_e32 vcc, v68, v32
	v_mov_b32_e32 v29, 0
	v_mov_b32_e32 v50, 0
	s_and_saveexec_b64 s[4:5], vcc
	s_cbranch_execz .LBB0_2508
	s_or_b32 s21, s20, 12
	v_sub_u32_e32 v24, s21, v32
	v_mul_i32_i24_e32 v24, 0x700, v24
	v_ashrrev_i32_e32 v25, 31, v24
	v_lshl_add_u64 v[24:25], v[24:25], 1, v[22:23]
	global_load_ushort v152, v[24:25], off
.LBB0_2508:
	s_or_b64 exec, exec, s[4:5]
	s_addk_i32 s6, 0x700
	v_lshl_add_u64 v[24:25], s[6:7], 1, v[22:23]
	global_load_ushort v44, v[24:25], off
	v_or_b32_e32 v62, 13, v26
	v_cmp_ge_u32_e32 vcc, v62, v32
	s_and_saveexec_b64 s[4:5], vcc
	s_cbranch_execz .LBB0_2510
	s_or_b32 s21, s20, 13
	v_sub_u32_e32 v24, s21, v32
	v_mul_i32_i24_e32 v24, 0x700, v24
	v_ashrrev_i32_e32 v25, 31, v24
	v_lshl_add_u64 v[24:25], v[24:25], 1, v[22:23]
	global_load_ushort v153, v[24:25], off
.LBB0_2510:
	s_or_b64 exec, exec, s[4:5]
	s_addk_i32 s6, 0x700
	v_lshl_add_u64 v[24:25], s[6:7], 1, v[22:23]
	global_load_ushort v42, v[24:25], off
	v_or_b32_e32 v60, 14, v26
	v_cmp_ge_u32_e32 vcc, v60, v32
	v_mov_b32_e32 v28, 0
	v_mov_b32_e32 v46, 0
	s_and_saveexec_b64 s[4:5], vcc
	s_cbranch_execz .LBB0_2512
	s_or_b32 s21, s20, 14
	v_sub_u32_e32 v24, s21, v32
	v_mul_i32_i24_e32 v24, 0x700, v24
	v_ashrrev_i32_e32 v25, 31, v24
	v_lshl_add_u64 v[24:25], v[24:25], 1, v[22:23]
	global_load_ushort v154, v[24:25], off
.LBB0_2512:
	s_or_b64 exec, exec, s[4:5]
	s_addk_i32 s6, 0x700
	v_lshl_add_u64 v[24:25], s[6:7], 1, v[22:23]
	global_load_ushort v41, v[24:25], off
	v_or_b32_e32 v57, 15, v26
	v_cmp_ge_u32_e32 vcc, v57, v32
	s_and_saveexec_b64 s[4:5], vcc
	s_cbranch_execz .LBB0_2481
	s_or_b32 s6, s20, 15
	v_sub_u32_e32 v24, s6, v32
	v_mul_i32_i24_e32 v24, 0x700, v24
	v_ashrrev_i32_e32 v25, 31, v24
	v_lshl_add_u64 v[24:25], v[24:25], 1, v[22:23]
	global_load_ushort v155, v[24:25], off
	s_branch .LBB0_2481
